# P0 x to bf16 loop hand-written and software-pipelined (next pass's 16 loads in flight while this pass converts and stores; v_cvt_pk_bf16_f32), on top of the pipelined act phase
# speedup vs baseline: 1.0136x; 1.0136x over previous
.LBB0_5:
	s_or_b64 exec, exec, s[30:31]
	s_mov_b32 s3, s53
	s_lshl_b64 s[30:31], s[2:3], 9
	v_mov_b32_e32 v10, v200
	v_writelane_b32 v246, s30, 0
	v_ashrrev_i32_e32 v11, 31, v10
	s_mov_b32 s52, s96
	v_writelane_b32 v246, s31, 1
	v_lshl_add_u64 v[12:13], s[30:31], 0, v[10:11]
	s_mov_b64 s[30:31], 0x800000
	s_lshl_b64 s[50:51], s[52:53], 12
	v_cmp_gt_u64_e32 vcc, s[30:31], v[12:13]
	s_and_saveexec_b64 s[30:31], vcc
	s_cbranch_execz .LBB0_8
	s_lshl_b64 s[34:35], s[52:53], 13
	s_lshl_b64 s[36:37], s[2:3], 13
	s_add_u32 s36, s26, s36
	s_addc_u32 s37, s27, s37
	v_lshl_add_u64 v[2:3], v[10:11], 4, s[36:37]
	s_mov_b64 s[36:37], 0x1000000
	v_lshl_add_u64 v[14:15], v[2:3], 0, s[36:37]
	s_lshl_b64 s[36:37], s[52:53], 16
	s_lshl_b64 s[38:39], s[2:3], 14
	s_add_u32 s38, s4, s38
	v_lshlrev_b64 v[2:3], 5, v[10:11]
	s_addc_u32 s39, s5, s39
	v_lshl_add_u64 v[16:17], s[38:39], 0, v[2:3]
	s_lshl_b64 s[38:39], s[52:53], 17
	s_lshl_b64 s[40:41], s[52:53], 14
	s_mov_b64 s[42:43], 0
	s_movk_i32 s47, 0x7fff
	s_mov_b32 s48, 0xffff0000
	s_mov_b64 s[44:45], 0x7fffff
	s_cmp_eq_u32 s96, 0x100
	s_cbranch_scc0 .LBB0_7
	v_mov_b64_e32 v[148:149], v[16:17]
	v_mov_b64_e32 v[150:151], v[14:15]
	v_mov_b64_e32 v[152:153], v[148:149]
	global_load_dwordx4 v[12:15], v[152:153], off
	global_load_dwordx4 v[16:19], v[152:153], off offset:16
	v_lshl_add_u64 v[152:153], v[152:153], 0, s[40:41]
	global_load_dwordx4 v[20:23], v[152:153], off
	global_load_dwordx4 v[24:27], v[152:153], off offset:16
	v_lshl_add_u64 v[152:153], v[152:153], 0, s[40:41]
	global_load_dwordx4 v[28:31], v[152:153], off
	global_load_dwordx4 v[32:35], v[152:153], off offset:16
	v_lshl_add_u64 v[152:153], v[152:153], 0, s[40:41]
	global_load_dwordx4 v[36:39], v[152:153], off
	global_load_dwordx4 v[40:43], v[152:153], off offset:16
	v_lshl_add_u64 v[152:153], v[152:153], 0, s[40:41]
	global_load_dwordx4 v[44:47], v[152:153], off
	global_load_dwordx4 v[48:51], v[152:153], off offset:16
	v_lshl_add_u64 v[152:153], v[152:153], 0, s[40:41]
	global_load_dwordx4 v[52:55], v[152:153], off
	global_load_dwordx4 v[56:59], v[152:153], off offset:16
	v_lshl_add_u64 v[152:153], v[152:153], 0, s[40:41]
	global_load_dwordx4 v[60:63], v[152:153], off
	global_load_dwordx4 v[64:67], v[152:153], off offset:16
	v_lshl_add_u64 v[152:153], v[152:153], 0, s[40:41]
	global_load_dwordx4 v[68:71], v[152:153], off
	global_load_dwordx4 v[72:75], v[152:153], off offset:16
	v_lshl_add_u64 v[148:149], v[148:149], 0, s[38:39]
	v_mov_b64_e32 v[152:153], v[148:149]
	global_load_dwordx4 v[76:79], v[152:153], off
	global_load_dwordx4 v[80:83], v[152:153], off offset:16
	v_lshl_add_u64 v[152:153], v[152:153], 0, s[40:41]
	global_load_dwordx4 v[84:87], v[152:153], off
	global_load_dwordx4 v[88:91], v[152:153], off offset:16
	v_lshl_add_u64 v[152:153], v[152:153], 0, s[40:41]
	global_load_dwordx4 v[92:95], v[152:153], off
	global_load_dwordx4 v[96:99], v[152:153], off offset:16
	v_lshl_add_u64 v[152:153], v[152:153], 0, s[40:41]
	global_load_dwordx4 v[100:103], v[152:153], off
	global_load_dwordx4 v[104:107], v[152:153], off offset:16
	v_lshl_add_u64 v[152:153], v[152:153], 0, s[40:41]
	global_load_dwordx4 v[108:111], v[152:153], off
	global_load_dwordx4 v[112:115], v[152:153], off offset:16
	v_lshl_add_u64 v[152:153], v[152:153], 0, s[40:41]
	global_load_dwordx4 v[116:119], v[152:153], off
	global_load_dwordx4 v[120:123], v[152:153], off offset:16
	v_lshl_add_u64 v[152:153], v[152:153], 0, s[40:41]
	global_load_dwordx4 v[124:127], v[152:153], off
	global_load_dwordx4 v[128:131], v[152:153], off offset:16
	v_lshl_add_u64 v[152:153], v[152:153], 0, s[40:41]
	global_load_dwordx4 v[132:135], v[152:153], off
	global_load_dwordx4 v[136:139], v[152:153], off offset:16
	v_lshl_add_u64 v[148:149], v[148:149], 0, s[38:39]
	s_waitcnt vmcnt(16)
	v_mov_b64_e32 v[154:155], v[150:151]
	v_cvt_pk_bf16_f32 v140, v12, v13
	v_cvt_pk_bf16_f32 v141, v14, v15
	v_cvt_pk_bf16_f32 v142, v16, v17
	v_cvt_pk_bf16_f32 v143, v18, v19
	global_store_dwordx4 v[154:155], v[140:143], off
	v_lshl_add_u64 v[154:155], v[154:155], 0, s[34:35]
	v_cvt_pk_bf16_f32 v144, v20, v21
	v_cvt_pk_bf16_f32 v145, v22, v23
	v_cvt_pk_bf16_f32 v146, v24, v25
	v_cvt_pk_bf16_f32 v147, v26, v27
	global_store_dwordx4 v[154:155], v[144:147], off
	v_lshl_add_u64 v[154:155], v[154:155], 0, s[34:35]
	v_cvt_pk_bf16_f32 v140, v28, v29
	v_cvt_pk_bf16_f32 v141, v30, v31
	v_cvt_pk_bf16_f32 v142, v32, v33
	v_cvt_pk_bf16_f32 v143, v34, v35
	global_store_dwordx4 v[154:155], v[140:143], off
	v_lshl_add_u64 v[154:155], v[154:155], 0, s[34:35]
	v_cvt_pk_bf16_f32 v144, v36, v37
	v_cvt_pk_bf16_f32 v145, v38, v39
	v_cvt_pk_bf16_f32 v146, v40, v41
	v_cvt_pk_bf16_f32 v147, v42, v43
	global_store_dwordx4 v[154:155], v[144:147], off
	v_lshl_add_u64 v[154:155], v[154:155], 0, s[34:35]
	v_cvt_pk_bf16_f32 v140, v44, v45
	v_cvt_pk_bf16_f32 v141, v46, v47
	v_cvt_pk_bf16_f32 v142, v48, v49
	v_cvt_pk_bf16_f32 v143, v50, v51
	global_store_dwordx4 v[154:155], v[140:143], off
	v_lshl_add_u64 v[154:155], v[154:155], 0, s[34:35]
	v_cvt_pk_bf16_f32 v144, v52, v53
	v_cvt_pk_bf16_f32 v145, v54, v55
	v_cvt_pk_bf16_f32 v146, v56, v57
	v_cvt_pk_bf16_f32 v147, v58, v59
	global_store_dwordx4 v[154:155], v[144:147], off
	v_lshl_add_u64 v[154:155], v[154:155], 0, s[34:35]
	v_cvt_pk_bf16_f32 v140, v60, v61
	v_cvt_pk_bf16_f32 v141, v62, v63
	v_cvt_pk_bf16_f32 v142, v64, v65
	v_cvt_pk_bf16_f32 v143, v66, v67
	global_store_dwordx4 v[154:155], v[140:143], off
	v_lshl_add_u64 v[154:155], v[154:155], 0, s[34:35]
	v_cvt_pk_bf16_f32 v144, v68, v69
	v_cvt_pk_bf16_f32 v145, v70, v71
	v_cvt_pk_bf16_f32 v146, v72, v73
	v_cvt_pk_bf16_f32 v147, v74, v75
	global_store_dwordx4 v[154:155], v[144:147], off
	v_lshl_add_u64 v[150:151], v[150:151], 0, s[36:37]
	v_mov_b64_e32 v[152:153], v[148:149]
	global_load_dwordx4 v[12:15], v[152:153], off
	global_load_dwordx4 v[16:19], v[152:153], off offset:16
	v_lshl_add_u64 v[152:153], v[152:153], 0, s[40:41]
	global_load_dwordx4 v[20:23], v[152:153], off
	global_load_dwordx4 v[24:27], v[152:153], off offset:16
	v_lshl_add_u64 v[152:153], v[152:153], 0, s[40:41]
	global_load_dwordx4 v[28:31], v[152:153], off
	global_load_dwordx4 v[32:35], v[152:153], off offset:16
	v_lshl_add_u64 v[152:153], v[152:153], 0, s[40:41]
	global_load_dwordx4 v[36:39], v[152:153], off
	global_load_dwordx4 v[40:43], v[152:153], off offset:16
	v_lshl_add_u64 v[152:153], v[152:153], 0, s[40:41]
	global_load_dwordx4 v[44:47], v[152:153], off
	global_load_dwordx4 v[48:51], v[152:153], off offset:16
	v_lshl_add_u64 v[152:153], v[152:153], 0, s[40:41]
	global_load_dwordx4 v[52:55], v[152:153], off
	global_load_dwordx4 v[56:59], v[152:153], off offset:16
	v_lshl_add_u64 v[152:153], v[152:153], 0, s[40:41]
	global_load_dwordx4 v[60:63], v[152:153], off
	global_load_dwordx4 v[64:67], v[152:153], off offset:16
	v_lshl_add_u64 v[152:153], v[152:153], 0, s[40:41]
	global_load_dwordx4 v[68:71], v[152:153], off
	global_load_dwordx4 v[72:75], v[152:153], off offset:16
	v_lshl_add_u64 v[148:149], v[148:149], 0, s[38:39]
	s_waitcnt vmcnt(24)
	v_mov_b64_e32 v[154:155], v[150:151]
	v_cvt_pk_bf16_f32 v140, v76, v77
	v_cvt_pk_bf16_f32 v141, v78, v79
	v_cvt_pk_bf16_f32 v142, v80, v81
	v_cvt_pk_bf16_f32 v143, v82, v83
	global_store_dwordx4 v[154:155], v[140:143], off
	v_lshl_add_u64 v[154:155], v[154:155], 0, s[34:35]
	v_cvt_pk_bf16_f32 v144, v84, v85
	v_cvt_pk_bf16_f32 v145, v86, v87
	v_cvt_pk_bf16_f32 v146, v88, v89
	v_cvt_pk_bf16_f32 v147, v90, v91
	global_store_dwordx4 v[154:155], v[144:147], off
	v_lshl_add_u64 v[154:155], v[154:155], 0, s[34:35]
	v_cvt_pk_bf16_f32 v140, v92, v93
	v_cvt_pk_bf16_f32 v141, v94, v95
	v_cvt_pk_bf16_f32 v142, v96, v97
	v_cvt_pk_bf16_f32 v143, v98, v99
	global_store_dwordx4 v[154:155], v[140:143], off
	v_lshl_add_u64 v[154:155], v[154:155], 0, s[34:35]
	v_cvt_pk_bf16_f32 v144, v100, v101
	v_cvt_pk_bf16_f32 v145, v102, v103
	v_cvt_pk_bf16_f32 v146, v104, v105
	v_cvt_pk_bf16_f32 v147, v106, v107
	global_store_dwordx4 v[154:155], v[144:147], off
	v_lshl_add_u64 v[154:155], v[154:155], 0, s[34:35]
	v_cvt_pk_bf16_f32 v140, v108, v109
	v_cvt_pk_bf16_f32 v141, v110, v111
	v_cvt_pk_bf16_f32 v142, v112, v113
	v_cvt_pk_bf16_f32 v143, v114, v115
	global_store_dwordx4 v[154:155], v[140:143], off
	v_lshl_add_u64 v[154:155], v[154:155], 0, s[34:35]
	v_cvt_pk_bf16_f32 v144, v116, v117
	v_cvt_pk_bf16_f32 v145, v118, v119
	v_cvt_pk_bf16_f32 v146, v120, v121
	v_cvt_pk_bf16_f32 v147, v122, v123
	global_store_dwordx4 v[154:155], v[144:147], off
	v_lshl_add_u64 v[154:155], v[154:155], 0, s[34:35]
	v_cvt_pk_bf16_f32 v140, v124, v125
	v_cvt_pk_bf16_f32 v141, v126, v127
	v_cvt_pk_bf16_f32 v142, v128, v129
	v_cvt_pk_bf16_f32 v143, v130, v131
	global_store_dwordx4 v[154:155], v[140:143], off
	v_lshl_add_u64 v[154:155], v[154:155], 0, s[34:35]
	v_cvt_pk_bf16_f32 v144, v132, v133
	v_cvt_pk_bf16_f32 v145, v134, v135
	v_cvt_pk_bf16_f32 v146, v136, v137
	v_cvt_pk_bf16_f32 v147, v138, v139
	global_store_dwordx4 v[154:155], v[144:147], off
	v_lshl_add_u64 v[150:151], v[150:151], 0, s[36:37]
	v_mov_b64_e32 v[152:153], v[148:149]
	global_load_dwordx4 v[76:79], v[152:153], off
	global_load_dwordx4 v[80:83], v[152:153], off offset:16
	v_lshl_add_u64 v[152:153], v[152:153], 0, s[40:41]
	global_load_dwordx4 v[84:87], v[152:153], off
	global_load_dwordx4 v[88:91], v[152:153], off offset:16
	v_lshl_add_u64 v[152:153], v[152:153], 0, s[40:41]
	global_load_dwordx4 v[92:95], v[152:153], off
	global_load_dwordx4 v[96:99], v[152:153], off offset:16
	v_lshl_add_u64 v[152:153], v[152:153], 0, s[40:41]
	global_load_dwordx4 v[100:103], v[152:153], off
	global_load_dwordx4 v[104:107], v[152:153], off offset:16
	v_lshl_add_u64 v[152:153], v[152:153], 0, s[40:41]
	global_load_dwordx4 v[108:111], v[152:153], off
	global_load_dwordx4 v[112:115], v[152:153], off offset:16
	v_lshl_add_u64 v[152:153], v[152:153], 0, s[40:41]
	global_load_dwordx4 v[116:119], v[152:153], off
	global_load_dwordx4 v[120:123], v[152:153], off offset:16
	v_lshl_add_u64 v[152:153], v[152:153], 0, s[40:41]
	global_load_dwordx4 v[124:127], v[152:153], off
	global_load_dwordx4 v[128:131], v[152:153], off offset:16
	v_lshl_add_u64 v[152:153], v[152:153], 0, s[40:41]
	global_load_dwordx4 v[132:135], v[152:153], off
	global_load_dwordx4 v[136:139], v[152:153], off offset:16
	v_lshl_add_u64 v[148:149], v[148:149], 0, s[38:39]
	s_waitcnt vmcnt(24)
	v_mov_b64_e32 v[154:155], v[150:151]
	v_cvt_pk_bf16_f32 v140, v12, v13
	v_cvt_pk_bf16_f32 v141, v14, v15
	v_cvt_pk_bf16_f32 v142, v16, v17
	v_cvt_pk_bf16_f32 v143, v18, v19
	global_store_dwordx4 v[154:155], v[140:143], off
	v_lshl_add_u64 v[154:155], v[154:155], 0, s[34:35]
	v_cvt_pk_bf16_f32 v144, v20, v21
	v_cvt_pk_bf16_f32 v145, v22, v23
	v_cvt_pk_bf16_f32 v146, v24, v25
	v_cvt_pk_bf16_f32 v147, v26, v27
	global_store_dwordx4 v[154:155], v[144:147], off
	v_lshl_add_u64 v[154:155], v[154:155], 0, s[34:35]
	v_cvt_pk_bf16_f32 v140, v28, v29
	v_cvt_pk_bf16_f32 v141, v30, v31
	v_cvt_pk_bf16_f32 v142, v32, v33
	v_cvt_pk_bf16_f32 v143, v34, v35
	global_store_dwordx4 v[154:155], v[140:143], off
	v_lshl_add_u64 v[154:155], v[154:155], 0, s[34:35]
	v_cvt_pk_bf16_f32 v144, v36, v37
	v_cvt_pk_bf16_f32 v145, v38, v39
	v_cvt_pk_bf16_f32 v146, v40, v41
	v_cvt_pk_bf16_f32 v147, v42, v43
	global_store_dwordx4 v[154:155], v[144:147], off
	v_lshl_add_u64 v[154:155], v[154:155], 0, s[34:35]
	v_cvt_pk_bf16_f32 v140, v44, v45
	v_cvt_pk_bf16_f32 v141, v46, v47
	v_cvt_pk_bf16_f32 v142, v48, v49
	v_cvt_pk_bf16_f32 v143, v50, v51
	global_store_dwordx4 v[154:155], v[140:143], off
	v_lshl_add_u64 v[154:155], v[154:155], 0, s[34:35]
	v_cvt_pk_bf16_f32 v144, v52, v53
	v_cvt_pk_bf16_f32 v145, v54, v55
	v_cvt_pk_bf16_f32 v146, v56, v57
	v_cvt_pk_bf16_f32 v147, v58, v59
	global_store_dwordx4 v[154:155], v[144:147], off
	v_lshl_add_u64 v[154:155], v[154:155], 0, s[34:35]
	v_cvt_pk_bf16_f32 v140, v60, v61
	v_cvt_pk_bf16_f32 v141, v62, v63
	v_cvt_pk_bf16_f32 v142, v64, v65
	v_cvt_pk_bf16_f32 v143, v66, v67
	global_store_dwordx4 v[154:155], v[140:143], off
	v_lshl_add_u64 v[154:155], v[154:155], 0, s[34:35]
	v_cvt_pk_bf16_f32 v144, v68, v69
	v_cvt_pk_bf16_f32 v145, v70, v71
	v_cvt_pk_bf16_f32 v146, v72, v73
	v_cvt_pk_bf16_f32 v147, v74, v75
	global_store_dwordx4 v[154:155], v[144:147], off
	v_lshl_add_u64 v[150:151], v[150:151], 0, s[36:37]
	v_mov_b64_e32 v[152:153], v[148:149]
	global_load_dwordx4 v[12:15], v[152:153], off
	global_load_dwordx4 v[16:19], v[152:153], off offset:16
	v_lshl_add_u64 v[152:153], v[152:153], 0, s[40:41]
	global_load_dwordx4 v[20:23], v[152:153], off
	global_load_dwordx4 v[24:27], v[152:153], off offset:16
	v_lshl_add_u64 v[152:153], v[152:153], 0, s[40:41]
	global_load_dwordx4 v[28:31], v[152:153], off
	global_load_dwordx4 v[32:35], v[152:153], off offset:16
	v_lshl_add_u64 v[152:153], v[152:153], 0, s[40:41]
	global_load_dwordx4 v[36:39], v[152:153], off
	global_load_dwordx4 v[40:43], v[152:153], off offset:16
	v_lshl_add_u64 v[152:153], v[152:153], 0, s[40:41]
	global_load_dwordx4 v[44:47], v[152:153], off
	global_load_dwordx4 v[48:51], v[152:153], off offset:16
	v_lshl_add_u64 v[152:153], v[152:153], 0, s[40:41]
	global_load_dwordx4 v[52:55], v[152:153], off
	global_load_dwordx4 v[56:59], v[152:153], off offset:16
	v_lshl_add_u64 v[152:153], v[152:153], 0, s[40:41]
	global_load_dwordx4 v[60:63], v[152:153], off
	global_load_dwordx4 v[64:67], v[152:153], off offset:16
	v_lshl_add_u64 v[152:153], v[152:153], 0, s[40:41]
	global_load_dwordx4 v[68:71], v[152:153], off
	global_load_dwordx4 v[72:75], v[152:153], off offset:16
	v_lshl_add_u64 v[148:149], v[148:149], 0, s[38:39]
	s_waitcnt vmcnt(24)
	v_mov_b64_e32 v[154:155], v[150:151]
	v_cvt_pk_bf16_f32 v140, v76, v77
	v_cvt_pk_bf16_f32 v141, v78, v79
	v_cvt_pk_bf16_f32 v142, v80, v81
	v_cvt_pk_bf16_f32 v143, v82, v83
	global_store_dwordx4 v[154:155], v[140:143], off
	v_lshl_add_u64 v[154:155], v[154:155], 0, s[34:35]
	v_cvt_pk_bf16_f32 v144, v84, v85
	v_cvt_pk_bf16_f32 v145, v86, v87
	v_cvt_pk_bf16_f32 v146, v88, v89
	v_cvt_pk_bf16_f32 v147, v90, v91
	global_store_dwordx4 v[154:155], v[144:147], off
	v_lshl_add_u64 v[154:155], v[154:155], 0, s[34:35]
	v_cvt_pk_bf16_f32 v140, v92, v93
	v_cvt_pk_bf16_f32 v141, v94, v95
	v_cvt_pk_bf16_f32 v142, v96, v97
	v_cvt_pk_bf16_f32 v143, v98, v99
	global_store_dwordx4 v[154:155], v[140:143], off
	v_lshl_add_u64 v[154:155], v[154:155], 0, s[34:35]
	v_cvt_pk_bf16_f32 v144, v100, v101
	v_cvt_pk_bf16_f32 v145, v102, v103
	v_cvt_pk_bf16_f32 v146, v104, v105
	v_cvt_pk_bf16_f32 v147, v106, v107
	global_store_dwordx4 v[154:155], v[144:147], off
	v_lshl_add_u64 v[154:155], v[154:155], 0, s[34:35]
	v_cvt_pk_bf16_f32 v140, v108, v109
	v_cvt_pk_bf16_f32 v141, v110, v111
	v_cvt_pk_bf16_f32 v142, v112, v113
	v_cvt_pk_bf16_f32 v143, v114, v115
	global_store_dwordx4 v[154:155], v[140:143], off
	v_lshl_add_u64 v[154:155], v[154:155], 0, s[34:35]
	v_cvt_pk_bf16_f32 v144, v116, v117
	v_cvt_pk_bf16_f32 v145, v118, v119
	v_cvt_pk_bf16_f32 v146, v120, v121
	v_cvt_pk_bf16_f32 v147, v122, v123
	global_store_dwordx4 v[154:155], v[144:147], off
	v_lshl_add_u64 v[154:155], v[154:155], 0, s[34:35]
	v_cvt_pk_bf16_f32 v140, v124, v125
	v_cvt_pk_bf16_f32 v141, v126, v127
	v_cvt_pk_bf16_f32 v142, v128, v129
	v_cvt_pk_bf16_f32 v143, v130, v131
	global_store_dwordx4 v[154:155], v[140:143], off
	v_lshl_add_u64 v[154:155], v[154:155], 0, s[34:35]
	v_cvt_pk_bf16_f32 v144, v132, v133
	v_cvt_pk_bf16_f32 v145, v134, v135
	v_cvt_pk_bf16_f32 v146, v136, v137
	v_cvt_pk_bf16_f32 v147, v138, v139
	global_store_dwordx4 v[154:155], v[144:147], off
	v_lshl_add_u64 v[150:151], v[150:151], 0, s[36:37]
	v_mov_b64_e32 v[152:153], v[148:149]
	global_load_dwordx4 v[76:79], v[152:153], off
	global_load_dwordx4 v[80:83], v[152:153], off offset:16
	v_lshl_add_u64 v[152:153], v[152:153], 0, s[40:41]
	global_load_dwordx4 v[84:87], v[152:153], off
	global_load_dwordx4 v[88:91], v[152:153], off offset:16
	v_lshl_add_u64 v[152:153], v[152:153], 0, s[40:41]
	global_load_dwordx4 v[92:95], v[152:153], off
	global_load_dwordx4 v[96:99], v[152:153], off offset:16
	v_lshl_add_u64 v[152:153], v[152:153], 0, s[40:41]
	global_load_dwordx4 v[100:103], v[152:153], off
	global_load_dwordx4 v[104:107], v[152:153], off offset:16
	v_lshl_add_u64 v[152:153], v[152:153], 0, s[40:41]
	global_load_dwordx4 v[108:111], v[152:153], off
	global_load_dwordx4 v[112:115], v[152:153], off offset:16
	v_lshl_add_u64 v[152:153], v[152:153], 0, s[40:41]
	global_load_dwordx4 v[116:119], v[152:153], off
	global_load_dwordx4 v[120:123], v[152:153], off offset:16
	v_lshl_add_u64 v[152:153], v[152:153], 0, s[40:41]
	global_load_dwordx4 v[124:127], v[152:153], off
	global_load_dwordx4 v[128:131], v[152:153], off offset:16
	v_lshl_add_u64 v[152:153], v[152:153], 0, s[40:41]
	global_load_dwordx4 v[132:135], v[152:153], off
	global_load_dwordx4 v[136:139], v[152:153], off offset:16
	v_lshl_add_u64 v[148:149], v[148:149], 0, s[38:39]
	s_waitcnt vmcnt(24)
	v_mov_b64_e32 v[154:155], v[150:151]
	v_cvt_pk_bf16_f32 v140, v12, v13
	v_cvt_pk_bf16_f32 v141, v14, v15
	v_cvt_pk_bf16_f32 v142, v16, v17
	v_cvt_pk_bf16_f32 v143, v18, v19
	global_store_dwordx4 v[154:155], v[140:143], off
	v_lshl_add_u64 v[154:155], v[154:155], 0, s[34:35]
	v_cvt_pk_bf16_f32 v144, v20, v21
	v_cvt_pk_bf16_f32 v145, v22, v23
	v_cvt_pk_bf16_f32 v146, v24, v25
	v_cvt_pk_bf16_f32 v147, v26, v27
	global_store_dwordx4 v[154:155], v[144:147], off
	v_lshl_add_u64 v[154:155], v[154:155], 0, s[34:35]
	v_cvt_pk_bf16_f32 v140, v28, v29
	v_cvt_pk_bf16_f32 v141, v30, v31
	v_cvt_pk_bf16_f32 v142, v32, v33
	v_cvt_pk_bf16_f32 v143, v34, v35
	global_store_dwordx4 v[154:155], v[140:143], off
	v_lshl_add_u64 v[154:155], v[154:155], 0, s[34:35]
	v_cvt_pk_bf16_f32 v144, v36, v37
	v_cvt_pk_bf16_f32 v145, v38, v39
	v_cvt_pk_bf16_f32 v146, v40, v41
	v_cvt_pk_bf16_f32 v147, v42, v43
	global_store_dwordx4 v[154:155], v[144:147], off
	v_lshl_add_u64 v[154:155], v[154:155], 0, s[34:35]
	v_cvt_pk_bf16_f32 v140, v44, v45
	v_cvt_pk_bf16_f32 v141, v46, v47
	v_cvt_pk_bf16_f32 v142, v48, v49
	v_cvt_pk_bf16_f32 v143, v50, v51
	global_store_dwordx4 v[154:155], v[140:143], off
	v_lshl_add_u64 v[154:155], v[154:155], 0, s[34:35]
	v_cvt_pk_bf16_f32 v144, v52, v53
	v_cvt_pk_bf16_f32 v145, v54, v55
	v_cvt_pk_bf16_f32 v146, v56, v57
	v_cvt_pk_bf16_f32 v147, v58, v59
	global_store_dwordx4 v[154:155], v[144:147], off
	v_lshl_add_u64 v[154:155], v[154:155], 0, s[34:35]
	v_cvt_pk_bf16_f32 v140, v60, v61
	v_cvt_pk_bf16_f32 v141, v62, v63
	v_cvt_pk_bf16_f32 v142, v64, v65
	v_cvt_pk_bf16_f32 v143, v66, v67
	global_store_dwordx4 v[154:155], v[140:143], off
	v_lshl_add_u64 v[154:155], v[154:155], 0, s[34:35]
	v_cvt_pk_bf16_f32 v144, v68, v69
	v_cvt_pk_bf16_f32 v145, v70, v71
	v_cvt_pk_bf16_f32 v146, v72, v73
	v_cvt_pk_bf16_f32 v147, v74, v75
	global_store_dwordx4 v[154:155], v[144:147], off
	v_lshl_add_u64 v[150:151], v[150:151], 0, s[36:37]
	v_mov_b64_e32 v[152:153], v[148:149]
	global_load_dwordx4 v[12:15], v[152:153], off
	global_load_dwordx4 v[16:19], v[152:153], off offset:16
	v_lshl_add_u64 v[152:153], v[152:153], 0, s[40:41]
	global_load_dwordx4 v[20:23], v[152:153], off
	global_load_dwordx4 v[24:27], v[152:153], off offset:16
	v_lshl_add_u64 v[152:153], v[152:153], 0, s[40:41]
	global_load_dwordx4 v[28:31], v[152:153], off
	global_load_dwordx4 v[32:35], v[152:153], off offset:16
	v_lshl_add_u64 v[152:153], v[152:153], 0, s[40:41]
	global_load_dwordx4 v[36:39], v[152:153], off
	global_load_dwordx4 v[40:43], v[152:153], off offset:16
	v_lshl_add_u64 v[152:153], v[152:153], 0, s[40:41]
	global_load_dwordx4 v[44:47], v[152:153], off
	global_load_dwordx4 v[48:51], v[152:153], off offset:16
	v_lshl_add_u64 v[152:153], v[152:153], 0, s[40:41]
	global_load_dwordx4 v[52:55], v[152:153], off
	global_load_dwordx4 v[56:59], v[152:153], off offset:16
	v_lshl_add_u64 v[152:153], v[152:153], 0, s[40:41]
	global_load_dwordx4 v[60:63], v[152:153], off
	global_load_dwordx4 v[64:67], v[152:153], off offset:16
	v_lshl_add_u64 v[152:153], v[152:153], 0, s[40:41]
	global_load_dwordx4 v[68:71], v[152:153], off
	global_load_dwordx4 v[72:75], v[152:153], off offset:16
	v_lshl_add_u64 v[148:149], v[148:149], 0, s[38:39]
	s_waitcnt vmcnt(24)
	v_mov_b64_e32 v[154:155], v[150:151]
	v_cvt_pk_bf16_f32 v140, v76, v77
	v_cvt_pk_bf16_f32 v141, v78, v79
	v_cvt_pk_bf16_f32 v142, v80, v81
	v_cvt_pk_bf16_f32 v143, v82, v83
	global_store_dwordx4 v[154:155], v[140:143], off
	v_lshl_add_u64 v[154:155], v[154:155], 0, s[34:35]
	v_cvt_pk_bf16_f32 v144, v84, v85
	v_cvt_pk_bf16_f32 v145, v86, v87
	v_cvt_pk_bf16_f32 v146, v88, v89
	v_cvt_pk_bf16_f32 v147, v90, v91
	global_store_dwordx4 v[154:155], v[144:147], off
	v_lshl_add_u64 v[154:155], v[154:155], 0, s[34:35]
	v_cvt_pk_bf16_f32 v140, v92, v93
	v_cvt_pk_bf16_f32 v141, v94, v95
	v_cvt_pk_bf16_f32 v142, v96, v97
	v_cvt_pk_bf16_f32 v143, v98, v99
	global_store_dwordx4 v[154:155], v[140:143], off
	v_lshl_add_u64 v[154:155], v[154:155], 0, s[34:35]
	v_cvt_pk_bf16_f32 v144, v100, v101
	v_cvt_pk_bf16_f32 v145, v102, v103
	v_cvt_pk_bf16_f32 v146, v104, v105
	v_cvt_pk_bf16_f32 v147, v106, v107
	global_store_dwordx4 v[154:155], v[144:147], off
	v_lshl_add_u64 v[154:155], v[154:155], 0, s[34:35]
	v_cvt_pk_bf16_f32 v140, v108, v109
	v_cvt_pk_bf16_f32 v141, v110, v111
	v_cvt_pk_bf16_f32 v142, v112, v113
	v_cvt_pk_bf16_f32 v143, v114, v115
	global_store_dwordx4 v[154:155], v[140:143], off
	v_lshl_add_u64 v[154:155], v[154:155], 0, s[34:35]
	v_cvt_pk_bf16_f32 v144, v116, v117
	v_cvt_pk_bf16_f32 v145, v118, v119
	v_cvt_pk_bf16_f32 v146, v120, v121
	v_cvt_pk_bf16_f32 v147, v122, v123
	global_store_dwordx4 v[154:155], v[144:147], off
	v_lshl_add_u64 v[154:155], v[154:155], 0, s[34:35]
	v_cvt_pk_bf16_f32 v140, v124, v125
	v_cvt_pk_bf16_f32 v141, v126, v127
	v_cvt_pk_bf16_f32 v142, v128, v129
	v_cvt_pk_bf16_f32 v143, v130, v131
	global_store_dwordx4 v[154:155], v[140:143], off
	v_lshl_add_u64 v[154:155], v[154:155], 0, s[34:35]
	v_cvt_pk_bf16_f32 v144, v132, v133
	v_cvt_pk_bf16_f32 v145, v134, v135
	v_cvt_pk_bf16_f32 v146, v136, v137
	v_cvt_pk_bf16_f32 v147, v138, v139
	global_store_dwordx4 v[154:155], v[144:147], off
	v_lshl_add_u64 v[150:151], v[150:151], 0, s[36:37]
	v_mov_b64_e32 v[152:153], v[148:149]
	global_load_dwordx4 v[76:79], v[152:153], off
	global_load_dwordx4 v[80:83], v[152:153], off offset:16
	v_lshl_add_u64 v[152:153], v[152:153], 0, s[40:41]
	global_load_dwordx4 v[84:87], v[152:153], off
	global_load_dwordx4 v[88:91], v[152:153], off offset:16
	v_lshl_add_u64 v[152:153], v[152:153], 0, s[40:41]
	global_load_dwordx4 v[92:95], v[152:153], off
	global_load_dwordx4 v[96:99], v[152:153], off offset:16
	v_lshl_add_u64 v[152:153], v[152:153], 0, s[40:41]
	global_load_dwordx4 v[100:103], v[152:153], off
	global_load_dwordx4 v[104:107], v[152:153], off offset:16
	v_lshl_add_u64 v[152:153], v[152:153], 0, s[40:41]
	global_load_dwordx4 v[108:111], v[152:153], off
	global_load_dwordx4 v[112:115], v[152:153], off offset:16
	v_lshl_add_u64 v[152:153], v[152:153], 0, s[40:41]
	global_load_dwordx4 v[116:119], v[152:153], off
	global_load_dwordx4 v[120:123], v[152:153], off offset:16
	v_lshl_add_u64 v[152:153], v[152:153], 0, s[40:41]
	global_load_dwordx4 v[124:127], v[152:153], off
	global_load_dwordx4 v[128:131], v[152:153], off offset:16
	v_lshl_add_u64 v[152:153], v[152:153], 0, s[40:41]
	global_load_dwordx4 v[132:135], v[152:153], off
	global_load_dwordx4 v[136:139], v[152:153], off offset:16
	v_lshl_add_u64 v[148:149], v[148:149], 0, s[38:39]
	s_waitcnt vmcnt(24)
	v_mov_b64_e32 v[154:155], v[150:151]
	v_cvt_pk_bf16_f32 v140, v12, v13
	v_cvt_pk_bf16_f32 v141, v14, v15
	v_cvt_pk_bf16_f32 v142, v16, v17
	v_cvt_pk_bf16_f32 v143, v18, v19
	global_store_dwordx4 v[154:155], v[140:143], off
	v_lshl_add_u64 v[154:155], v[154:155], 0, s[34:35]
	v_cvt_pk_bf16_f32 v144, v20, v21
	v_cvt_pk_bf16_f32 v145, v22, v23
	v_cvt_pk_bf16_f32 v146, v24, v25
	v_cvt_pk_bf16_f32 v147, v26, v27
	global_store_dwordx4 v[154:155], v[144:147], off
	v_lshl_add_u64 v[154:155], v[154:155], 0, s[34:35]
	v_cvt_pk_bf16_f32 v140, v28, v29
	v_cvt_pk_bf16_f32 v141, v30, v31
	v_cvt_pk_bf16_f32 v142, v32, v33
	v_cvt_pk_bf16_f32 v143, v34, v35
	global_store_dwordx4 v[154:155], v[140:143], off
	v_lshl_add_u64 v[154:155], v[154:155], 0, s[34:35]
	v_cvt_pk_bf16_f32 v144, v36, v37
	v_cvt_pk_bf16_f32 v145, v38, v39
	v_cvt_pk_bf16_f32 v146, v40, v41
	v_cvt_pk_bf16_f32 v147, v42, v43
	global_store_dwordx4 v[154:155], v[144:147], off
	v_lshl_add_u64 v[154:155], v[154:155], 0, s[34:35]
	v_cvt_pk_bf16_f32 v140, v44, v45
	v_cvt_pk_bf16_f32 v141, v46, v47
	v_cvt_pk_bf16_f32 v142, v48, v49
	v_cvt_pk_bf16_f32 v143, v50, v51
	global_store_dwordx4 v[154:155], v[140:143], off
	v_lshl_add_u64 v[154:155], v[154:155], 0, s[34:35]
	v_cvt_pk_bf16_f32 v144, v52, v53
	v_cvt_pk_bf16_f32 v145, v54, v55
	v_cvt_pk_bf16_f32 v146, v56, v57
	v_cvt_pk_bf16_f32 v147, v58, v59
	global_store_dwordx4 v[154:155], v[144:147], off
	v_lshl_add_u64 v[154:155], v[154:155], 0, s[34:35]
	v_cvt_pk_bf16_f32 v140, v60, v61
	v_cvt_pk_bf16_f32 v141, v62, v63
	v_cvt_pk_bf16_f32 v142, v64, v65
	v_cvt_pk_bf16_f32 v143, v66, v67
	global_store_dwordx4 v[154:155], v[140:143], off
	v_lshl_add_u64 v[154:155], v[154:155], 0, s[34:35]
	v_cvt_pk_bf16_f32 v144, v68, v69
	v_cvt_pk_bf16_f32 v145, v70, v71
	v_cvt_pk_bf16_f32 v146, v72, v73
	v_cvt_pk_bf16_f32 v147, v74, v75
	global_store_dwordx4 v[154:155], v[144:147], off
	v_lshl_add_u64 v[150:151], v[150:151], 0, s[36:37]
	s_waitcnt vmcnt(8)
	v_mov_b64_e32 v[154:155], v[150:151]
	v_cvt_pk_bf16_f32 v140, v76, v77
	v_cvt_pk_bf16_f32 v141, v78, v79
	v_cvt_pk_bf16_f32 v142, v80, v81
	v_cvt_pk_bf16_f32 v143, v82, v83
	global_store_dwordx4 v[154:155], v[140:143], off
	v_lshl_add_u64 v[154:155], v[154:155], 0, s[34:35]
	v_cvt_pk_bf16_f32 v144, v84, v85
	v_cvt_pk_bf16_f32 v145, v86, v87
	v_cvt_pk_bf16_f32 v146, v88, v89
	v_cvt_pk_bf16_f32 v147, v90, v91
	global_store_dwordx4 v[154:155], v[144:147], off
	v_lshl_add_u64 v[154:155], v[154:155], 0, s[34:35]
	v_cvt_pk_bf16_f32 v140, v92, v93
	v_cvt_pk_bf16_f32 v141, v94, v95
	v_cvt_pk_bf16_f32 v142, v96, v97
	v_cvt_pk_bf16_f32 v143, v98, v99
	global_store_dwordx4 v[154:155], v[140:143], off
	v_lshl_add_u64 v[154:155], v[154:155], 0, s[34:35]
	v_cvt_pk_bf16_f32 v144, v100, v101
	v_cvt_pk_bf16_f32 v145, v102, v103
	v_cvt_pk_bf16_f32 v146, v104, v105
	v_cvt_pk_bf16_f32 v147, v106, v107
	global_store_dwordx4 v[154:155], v[144:147], off
	v_lshl_add_u64 v[154:155], v[154:155], 0, s[34:35]
	v_cvt_pk_bf16_f32 v140, v108, v109
	v_cvt_pk_bf16_f32 v141, v110, v111
	v_cvt_pk_bf16_f32 v142, v112, v113
	v_cvt_pk_bf16_f32 v143, v114, v115
	global_store_dwordx4 v[154:155], v[140:143], off
	v_lshl_add_u64 v[154:155], v[154:155], 0, s[34:35]
	v_cvt_pk_bf16_f32 v144, v116, v117
	v_cvt_pk_bf16_f32 v145, v118, v119
	v_cvt_pk_bf16_f32 v146, v120, v121
	v_cvt_pk_bf16_f32 v147, v122, v123
	global_store_dwordx4 v[154:155], v[144:147], off
	v_lshl_add_u64 v[154:155], v[154:155], 0, s[34:35]
	v_cvt_pk_bf16_f32 v140, v124, v125
	v_cvt_pk_bf16_f32 v141, v126, v127
	v_cvt_pk_bf16_f32 v142, v128, v129
	v_cvt_pk_bf16_f32 v143, v130, v131
	global_store_dwordx4 v[154:155], v[140:143], off
	v_lshl_add_u64 v[154:155], v[154:155], 0, s[34:35]
	v_cvt_pk_bf16_f32 v144, v132, v133
	v_cvt_pk_bf16_f32 v145, v134, v135
	v_cvt_pk_bf16_f32 v146, v136, v137
	v_cvt_pk_bf16_f32 v147, v138, v139
	global_store_dwordx4 v[154:155], v[144:147], off
	s_branch .LBB0_8
	s_nop 0
	s_nop 0
	s_nop 0
	s_nop 0
	s_nop 0
	s_nop 0
	s_nop 0
	s_nop 0
	s_nop 0
	s_nop 0
	s_nop 0
	s_nop 0
	s_nop 0
	s_nop 0
	s_nop 0
	s_nop 0
	s_nop 0
	s_nop 0
	s_nop 0
	s_nop 0
	s_nop 0
	s_nop 0
	s_nop 0
	s_nop 0
	s_nop 0
	s_nop 0
	s_nop 0
	s_nop 0
	s_nop 0
	s_nop 0
	s_nop 0
	s_nop 0
	s_nop 0
	s_nop 0
	s_nop 0
	s_nop 0
